# mixer-A tile-loop head: redundant second lane-id recompute removed (2 fewer VALU after the barrier)
# baseline (speedup 1.0000x reference)
.LBB0_407:
	v_mbcnt_lo_u32_b32 v128, -1, 0
	v_mbcnt_hi_u32_b32 v128, -1, v128
	s_add_i32 s7, s7, 0
	v_bfe_u32 v129, v128, 2, 2
	v_lshrrev_b32_e32 v130, 3, v128
	v_bfe_u32 v132, v128, 1, 1
	v_and_or_b32 v131, v130, s64, v129
	v_and_or_b32 v130, v130, 2, v132
	v_lshlrev_b32_e32 v133, 3, v128
	v_lshlrev_b32_e32 v131, 8, v131
	v_lshlrev_b32_e32 v130, 4, v130
	v_and_b32_e32 v133, 8, v133
	v_or3_b32 v160, v130, v131, v133
	v_lshlrev_b32_e32 v162, 6, v129
	v_or_b32_e32 v163, v160, v162
	v_ashrrev_i32_e32 v129, 5, v128
	v_lshlrev_b32_e32 v130, 7, v128
	v_lshrrev_b32_e32 v133, 1, v128
	v_and_b32_e32 v132, 0xf80, v130
	v_bitop3_b32 v128, v133, v129, 7 bitop3:0x6c
	v_lshl_add_u32 v134, v128, 4, v132
	v_add_u32_e32 v128, 2, v129
	v_bitop3_b32 v128, v128, v133, 7 bitop3:0x78
	v_lshl_add_u32 v136, v128, 4, v132
	v_add_u32_e32 v128, 4, v129
	v_bitop3_b32 v128, v128, v133, 7 bitop3:0x78
	v_add_u32_e32 v207, s7, v134
	v_lshl_add_u32 v168, v128, 4, v132
	v_add_u32_e32 v135, 6, v129
	ds_read_b128 v[128:131], v207
	v_bitop3_b32 v133, v135, v133, 7 bitop3:0x78
	v_add_u32_e32 v224, s48, v134
	v_add_u32_e32 v225, s7, v136
	v_lshl_add_u32 v169, v133, 4, v132
	ds_read_b128 v[132:135], v224
	v_add_u32_e32 v226, s48, v136
	ds_read_b128 v[136:139], v225
	ds_read_b128 v[140:143], v226
	v_bitop3_b32 v203, v160, s37, v162 bitop3:0x36
	v_bitop3_b32 v206, v160, s41, v162 bitop3:0x36
	s_waitcnt lgkmcnt(2)
	v_mfma_f32_32x32x16_bf16 v[144:159], v[128:131], v[132:135], 0
	v_add_u32_e32 v227, s7, v168
	v_add_u32_e32 v228, s48, v168
	ds_read_b128 v[128:131], v227
	ds_read_b128 v[132:135], v228
	s_waitcnt lgkmcnt(2)
	v_mfma_f32_32x32x16_bf16 v[144:159], v[136:139], v[140:143], v[144:159]
	v_add_u32_e32 v230, s7, v169
	v_add_u32_e32 v232, s48, v169
	ds_read_b128 v[136:139], v230
	ds_read_b128 v[140:143], v232
	s_waitcnt lgkmcnt(2)
	v_mfma_f32_32x32x16_bf16 v[144:159], v[128:131], v[132:135], v[144:159]
	ds_read_b128 v[128:131], v207 offset:8192
	ds_read_b128 v[132:135], v224 offset:4096
	s_waitcnt lgkmcnt(2)
	v_mfma_f32_32x32x16_bf16 v[144:159], v[136:139], v[140:143], v[144:159]
	ds_read_b128 v[178:181], v225 offset:8192
	ds_read_b128 v[182:185], v226 offset:4096
	s_waitcnt lgkmcnt(2)
	v_mfma_f32_32x32x16_bf16 v[128:143], v[128:131], v[132:135], 0
	s_nop 7
	v_exp_f32_e32 v173, v144
	v_exp_f32_e32 v169, v145
	v_exp_f32_e32 v177, v146
	v_exp_f32_e32 v171, v147
	ds_read_b128 v[144:147], v227 offset:8192
	ds_read_b128 v[190:193], v228 offset:4096
	s_waitcnt lgkmcnt(2)
	v_mfma_f32_32x32x16_bf16 v[128:143], v[178:181], v[182:185], v[128:143]
	v_exp_f32_e32 v183, v148
	v_exp_f32_e32 v175, v149
	v_exp_f32_e32 v189, v150
	v_exp_f32_e32 v179, v151
	ds_read_b128 v[148:151], v230 offset:8192
	ds_read_b128 v[196:199], v232 offset:4096
	s_waitcnt lgkmcnt(2)
	v_mfma_f32_32x32x16_bf16 v[128:143], v[144:147], v[190:193], v[128:143]
	v_exp_f32_e32 v193, v152
	v_exp_f32_e32 v181, v153
	v_exp_f32_e32 v195, v154
	v_exp_f32_e32 v187, v155
	s_waitcnt lgkmcnt(0)
	v_mfma_f32_32x32x16_bf16 v[128:143], v[148:151], v[196:199], v[128:143]
	v_exp_f32_e32 v197, v156
	v_exp_f32_e32 v185, v157
	v_exp_f32_e32 v199, v158
	v_exp_f32_e32 v191, v159
	s_cmp_eq_u32 s4, 0x3f0000
	s_cbranch_scc1 .Lattn_nodma_a
	v_mov_b32_e32 v213, 0
	v_add_u32_e32 v212, s4, v202
	s_xor_b32 s8, s7, 0x4000
	v_lshl_add_u64 v[208:209], v[212:213], 1, s[66:67]
	s_add_i32 s9, s49, s8
	s_mov_b32 s10, m0
	s_mov_b32 m0, s9
	s_nop 0
	global_load_lds_dwordx4 v[208:209], off
	s_mov_b32 m0, s10
	v_add_u32_e32 v210, s4, v201
	v_lshl_add_u64 v[208:209], v[208:209], 0, s[38:39]
	s_add_i32 s9, s33, s8
	s_mov_b32 s10, m0
	s_mov_b32 m0, s9
	s_nop 0
	global_load_lds_dwordx4 v[208:209], off
	s_mov_b32 m0, s10
	v_add_u32_e32 v212, 0x10000, v210
	v_lshl_add_u64 v[208:209], v[212:213], 1, s[68:69]
	s_add_i32 s9, s54, s8
	s_mov_b32 s10, m0
	s_mov_b32 m0, s9
	s_nop 0
	global_load_lds_dwordx4 v[208:209], off
	s_mov_b32 m0, s10
	v_add_u32_e32 v212, 0x18000, v210
	v_lshl_add_u64 v[208:209], v[212:213], 1, s[68:69]
	s_add_i32 s8, s47, s8
	s_mov_b32 s9, m0
	s_mov_b32 m0, s8
	s_nop 0
	global_load_lds_dwordx4 v[208:209], off
	s_mov_b32 m0, s9
